# attention output tiles staged through LDS into coalesced dwordx4 stores
# speedup vs baseline: 1.0044x; 1.0044x over previous
; DI unsigned cvt_pk_bf16(float lo, float hi) { unsigned r; asm volatile("v_cvt_pk_bf16_f32 %0, %1, %2" : "=v"(r) : "v"(lo), "v"(hi)); return r; }
; DI void attn_phase(const Params& p) {
;     ...
; #pragma unroll
;     for (int hh = 0; hh < 2; ++hh) {
;       const float inv = 1.0f / lrun[hh];
;       bf16_t* op = o + (size_t)(t0 + r) * 1024 + (head0 + hh) * 64 + 4 * h;
; #pragma unroll
;       for (int gq = 0; gq < 4; ++gq) {
;         u32x2 a, b;
;         a.x = cvt_pk_bf16(o0[hh][4 * gq] * inv, o0[hh][4 * gq + 1] * inv); a.y = cvt_pk_bf16(o0[hh][4 * gq + 2] * inv, o0[hh][4 * gq + 3] * inv);
;         b.x = cvt_pk_bf16(o1[hh][4 * gq] * inv, o1[hh][4 * gq + 1] * inv); b.y = cvt_pk_bf16(o1[hh][4 * gq + 2] * inv, o1[hh][4 * gq + 3] * inv);
;         *(u32x2*)(op + 8 * gq) = a; *(u32x2*)(op + 32 + 8 * gq) = b;
;       }
;     }
.LBB0_231:
	s_or_b64 exec, exec, s[10:11]
	v_div_scale_f32 v66, s[6:7], v88, v88, 1.0
	v_rcp_f32_e32 v67, v66
	v_ashrrev_i32_e32 v163, 31, v162
	v_lshlrev_b64 v[64:65], 11, v[162:163]
	v_lshl_add_u64 v[64:65], v[160:161], 0, v[64:65]
	v_fma_f32 v68, -v66, v67, 1.0
	v_fmac_f32_e32 v67, v68, v67
	v_div_scale_f32 v68, vcc, 1.0, v88, 1.0
	v_mul_f32_e32 v69, v68, v67
	v_fma_f32 v70, -v66, v69, v68
	v_fmac_f32_e32 v69, v70, v67
	v_fma_f32 v66, -v66, v69, v68
	v_div_fmas_f32 v66, v66, v67, v69
	v_div_fixup_f32 v68, v66, v88, 1.0
	v_mul_f32_e32 v48, v48, v68
	v_mul_f32_e32 v49, v49, v68
	v_lshlrev_b32_e32 v66, 6, v164
	v_cvt_pk_bf16_f32 v48, v48, v49
	v_mul_f32_e32 v49, v50, v68
	v_mul_f32_e32 v32, v32, v68
	v_mul_f32_e32 v33, v33, v68
	v_ashrrev_i32_e32 v67, 31, v66
	v_mul_f32_e32 v50, v51, v68
	v_cvt_pk_bf16_f32 v49, v49, v50
	v_cvt_pk_bf16_f32 v32, v32, v33
	v_mul_f32_e32 v33, v34, v68
	v_lshl_add_u64 v[66:67], v[66:67], 1, v[64:65]
	v_mul_f32_e32 v34, v35, v68
	v_cvt_pk_bf16_f32 v33, v33, v34
	v_mbcnt_lo_u32_b32 v221, -1, 0
	v_mbcnt_hi_u32_b32 v221, -1, v221
	v_readlane_b32 s100, v255, 12
	v_and_b32_e32 v222, 31, v221
	v_lshrrev_b32_e32 v223, 5, v221
	v_lshrrev_b32_e32 v224, 3, v221
	v_and_b32_e32 v225, 7, v221
	v_mov_b32_e32 v226, s100
	v_mul_u32_u24_e32 v226, 0x44, v226
	v_add_u32_e32 v226, 0x1a000, v226
	v_mul_u32_u24_e32 v227, 0x88, v222
	v_lshl_add_u32 v227, v223, 3, v227
	v_add_u32_e32 v227, v226, v227
	v_mul_u32_u24_e32 v228, 0x88, v224
	v_lshl_add_u32 v228, v225, 4, v228
	v_add_u32_e32 v228, v226, v228
	v_sub_u32_e32 v230, v224, v222
	v_lshlrev_b32_e32 v230, 11, v230
	v_lshl_add_u32 v230, v225, 4, v230
	v_lshlrev_b32_e32 v223, 3, v223
	v_sub_u32_e32 v230, v230, v223
	v_ashrrev_i32_e32 v231, 31, v230
	v_mov_b32_e32 v250, 0x4000
	v_mov_b32_e32 v251, 0
	ds_write_b64 v227, v[48:49]
	ds_write_b64 v227, v[32:33] offset:64
	v_mul_f32_e32 v32, v52, v68
	v_mul_f32_e32 v33, v53, v68
	v_cvt_pk_bf16_f32 v32, v32, v33
	v_mul_f32_e32 v33, v54, v68
	v_mul_f32_e32 v34, v55, v68
	v_cvt_pk_bf16_f32 v33, v33, v34
	v_mul_f32_e32 v34, v36, v68
	v_mul_f32_e32 v35, v37, v68
	v_cvt_pk_bf16_f32 v34, v34, v35
	v_mul_f32_e32 v35, v38, v68
	v_mul_f32_e32 v36, v39, v68
	v_cvt_pk_bf16_f32 v35, v35, v36
	ds_write_b64 v227, v[32:33] offset:16
	ds_write_b64 v227, v[34:35] offset:80
	v_mul_f32_e32 v32, v56, v68
	v_mul_f32_e32 v33, v57, v68
	v_cvt_pk_bf16_f32 v32, v32, v33
	v_mul_f32_e32 v33, v58, v68
	v_mul_f32_e32 v34, v59, v68
	v_cvt_pk_bf16_f32 v33, v33, v34
	v_mul_f32_e32 v34, v40, v68
	v_mul_f32_e32 v35, v41, v68
	v_cvt_pk_bf16_f32 v34, v34, v35
	v_mul_f32_e32 v35, v42, v68
	v_div_scale_f32 v37, s[6:7], v72, v72, 1.0
	v_mul_f32_e32 v36, v43, v68
	v_cvt_pk_bf16_f32 v35, v35, v36
	ds_write_b64 v227, v[32:33] offset:32
	ds_write_b64 v227, v[34:35] offset:96
	v_mul_f32_e32 v32, v60, v68
	v_mul_f32_e32 v33, v61, v68
	v_rcp_f32_e32 v38, v37
	v_cvt_pk_bf16_f32 v32, v32, v33
	v_mul_f32_e32 v33, v62, v68
	v_mul_f32_e32 v34, v63, v68
	v_cvt_pk_bf16_f32 v33, v33, v34
	v_mul_f32_e32 v34, v44, v68
	v_mul_f32_e32 v35, v45, v68
	v_cvt_pk_bf16_f32 v34, v34, v35
	v_mul_f32_e32 v35, v46, v68
	v_mul_f32_e32 v36, v47, v68
	v_cvt_pk_bf16_f32 v35, v35, v36
	ds_write_b64 v227, v[32:33] offset:48
	ds_write_b64 v227, v[34:35] offset:112
	s_waitcnt lgkmcnt(0)
	ds_read_b128 v[232:235], v228
	ds_read_b128 v[236:239], v228 offset:1088
	ds_read_b128 v[240:243], v228 offset:2176
	ds_read_b128 v[244:247], v228 offset:3264
	v_lshl_add_u64 v[204:205], v[66:67], 0, v[230:231]
	v_lshl_add_u64 v[208:209], v[204:205], 0, v[250:251]
	v_lshl_add_u64 v[210:211], v[208:209], 0, v[250:251]
	v_lshl_add_u64 v[248:249], v[210:211], 0, v[250:251]
	s_waitcnt lgkmcnt(0)
	global_store_dwordx4 v[204:205], v[232:235], off
	global_store_dwordx4 v[208:209], v[236:239], off
	global_store_dwordx4 v[210:211], v[240:243], off
	global_store_dwordx4 v[248:249], v[244:247], off
	s_nop 1
	v_fma_f32 v32, -v37, v38, 1.0
	v_fmac_f32_e32 v38, v32, v38
	v_div_scale_f32 v32, vcc, 1.0, v72, 1.0
	v_mul_f32_e32 v33, v32, v38
	v_fma_f32 v34, -v37, v33, v32
	v_fmac_f32_e32 v33, v34, v38
	v_fma_f32 v32, -v37, v33, v32
	v_div_fmas_f32 v32, v32, v38, v33
	v_div_fixup_f32 v34, v32, v72, 1.0
	v_mul_f32_e32 v0, v0, v34
	v_mul_f32_e32 v1, v1, v34
	v_lshlrev_b32_e32 v32, 6, v185
	v_cvt_pk_bf16_f32 v0, v0, v1
	v_mul_f32_e32 v1, v2, v34
	v_mul_f32_e32 v2, v3, v34
	v_ashrrev_i32_e32 v33, 31, v32
	v_cvt_pk_bf16_f32 v1, v1, v2
	v_mul_f32_e32 v2, v16, v34
	v_mul_f32_e32 v3, v17, v34
	v_lshl_add_u64 v[32:33], v[32:33], 1, v[64:65]
	v_cvt_pk_bf16_f32 v2, v2, v3
	v_mul_f32_e32 v3, v18, v34
	v_mul_f32_e32 v16, v19, v34
	v_cvt_pk_bf16_f32 v3, v3, v16
	ds_write_b64 v227, v[0:1]
	ds_write_b64 v227, v[2:3] offset:64
	v_mul_f32_e32 v0, v4, v34
	v_mul_f32_e32 v1, v5, v34
	v_cvt_pk_bf16_f32 v0, v0, v1
	v_mul_f32_e32 v1, v6, v34
	v_mul_f32_e32 v2, v7, v34
	v_cvt_pk_bf16_f32 v1, v1, v2
	v_mul_f32_e32 v2, v20, v34
	v_mul_f32_e32 v3, v21, v34
	v_cvt_pk_bf16_f32 v2, v2, v3
	v_mul_f32_e32 v3, v22, v34
	v_mul_f32_e32 v4, v23, v34
	v_cvt_pk_bf16_f32 v3, v3, v4
	ds_write_b64 v227, v[0:1] offset:16
	ds_write_b64 v227, v[2:3] offset:80
	v_mul_f32_e32 v0, v8, v34
	v_mul_f32_e32 v1, v9, v34
	v_cvt_pk_bf16_f32 v0, v0, v1
	v_mul_f32_e32 v1, v10, v34
	v_mul_f32_e32 v2, v11, v34
	v_cvt_pk_bf16_f32 v1, v1, v2
	v_mul_f32_e32 v2, v24, v34
	v_mul_f32_e32 v3, v25, v34
	v_cvt_pk_bf16_f32 v2, v2, v3
	v_mul_f32_e32 v3, v26, v34
	v_mul_f32_e32 v4, v27, v34
	v_cvt_pk_bf16_f32 v3, v3, v4
	ds_write_b64 v227, v[0:1] offset:32
	ds_write_b64 v227, v[2:3] offset:96
	v_mul_f32_e32 v0, v12, v34
	v_mul_f32_e32 v1, v13, v34
	v_cvt_pk_bf16_f32 v0, v0, v1
	v_mul_f32_e32 v1, v14, v34
	v_mul_f32_e32 v2, v15, v34
	v_cvt_pk_bf16_f32 v1, v1, v2
	v_mul_f32_e32 v2, v28, v34
	v_mul_f32_e32 v3, v29, v34
	v_cvt_pk_bf16_f32 v2, v2, v3
	v_mul_f32_e32 v3, v30, v34
	v_mul_f32_e32 v4, v31, v34
	v_cvt_pk_bf16_f32 v3, v3, v4
	ds_write_b64 v227, v[0:1] offset:48
	ds_write_b64 v227, v[2:3] offset:112
	s_waitcnt lgkmcnt(0)
	ds_read_b128 v[232:235], v228
	ds_read_b128 v[236:239], v228 offset:1088
	ds_read_b128 v[240:243], v228 offset:2176
	ds_read_b128 v[244:247], v228 offset:3264
	v_lshl_add_u64 v[204:205], v[32:33], 0, v[230:231]
	v_lshl_add_u64 v[208:209], v[204:205], 0, v[250:251]
	v_lshl_add_u64 v[210:211], v[208:209], 0, v[250:251]
	v_lshl_add_u64 v[248:249], v[210:211], 0, v[250:251]
	s_waitcnt lgkmcnt(0)
	global_store_dwordx4 v[204:205], v[232:235], off
	global_store_dwordx4 v[208:209], v[236:239], off
	global_store_dwordx4 v[210:211], v[240:243], off
	global_store_dwordx4 v[248:249], v[244:247], off
	s_nop 1
	s_load_dword s6, s[88:89], 0x0
	s_waitcnt lgkmcnt(0)
	s_add_i32 s2, s6, s2
	s_cmpk_gt_i32 s2, 0x3ff
	s_cbranch_scc1 .LBB0_245
